# v14: v9 + grid barrier direct release (globally last arriver bumps every XCC generation word; XCC leaders no longer poll TOP)
# speedup vs baseline: 1.0022x; 1.0022x over previous
.Lxb0_go:
	v_add_u32_e32 v246, 0x1400, v245
	global_atomic_add v248, v246, v247, s[60:61] sc0
	v_add_u32_e32 v249, 1, v244
	ds_write_b32 v241, v249 offset:8
	v_mul_lo_u32 v250, v249, v242
	v_mul_lo_u32 v251, v249, v243
	v_add_u32_e32 v253, 0x2400, v245
	v_mov_b32_e32 v252, 0
	s_waitcnt vmcnt(0)
	buffer_inv sc1
	v_add_u32_e32 v248, 1, v248
	v_cmp_eq_u32_e32 vcc, v248, v250
	s_cbranch_vccz .Lxb0_wait
	buffer_wbl2 sc1
	s_waitcnt vmcnt(0)
	v_mov_b32_e32 v246, 0x3400
	global_atomic_add v248, v246, v247, s[60:61] sc0
	s_waitcnt vmcnt(0)
	v_add_u32_e32 v248, 1, v248
	v_cmp_ge_u32_e32 vcc, v248, v251
	s_cbranch_vccz .Lxb0_wait
	v_mov_b32_e32 v246, 0x2400
	global_atomic_add v246, v247, s[60:61]
	global_atomic_add v246, v247, s[60:61] offset:256
	global_atomic_add v246, v247, s[60:61] offset:512
	global_atomic_add v246, v247, s[60:61] offset:768
	global_atomic_add v246, v247, s[60:61] offset:1024
	global_atomic_add v246, v247, s[60:61] offset:1280
	global_atomic_add v246, v247, s[60:61] offset:1536
	global_atomic_add v246, v247, s[60:61] offset:1792
	global_atomic_add v246, v247, s[60:61] offset:2048
	global_atomic_add v246, v247, s[60:61] offset:2304
	global_atomic_add v246, v247, s[60:61] offset:2560
	global_atomic_add v246, v247, s[60:61] offset:2816
	global_atomic_add v246, v247, s[60:61] offset:3072
	global_atomic_add v246, v247, s[60:61] offset:3328
	global_atomic_add v246, v247, s[60:61] offset:3584
	global_atomic_add v246, v247, s[60:61] offset:3840
	s_branch .Lxb0_done

.Lxb2_go:
	v_add_u32_e32 v246, 0x1400, v245
	global_atomic_add v248, v246, v247, s[60:61] sc0
	v_add_u32_e32 v249, 1, v244
	ds_write_b32 v241, v249 offset:8
	v_mul_lo_u32 v250, v249, v242
	v_mul_lo_u32 v251, v249, v243
	v_add_u32_e32 v253, 0x2400, v245
	v_mov_b32_e32 v252, 0
	s_waitcnt vmcnt(0)
	buffer_inv sc1
	v_add_u32_e32 v248, 1, v248
	v_cmp_eq_u32_e32 vcc, v248, v250
	s_cbranch_vccz .Lxb2_wait
	s_waitcnt vmcnt(0)
	v_mov_b32_e32 v246, 0x3400
	global_atomic_add v248, v246, v247, s[60:61] sc0
	s_waitcnt vmcnt(0)
	v_add_u32_e32 v248, 1, v248
	v_cmp_ge_u32_e32 vcc, v248, v251
	s_cbranch_vccz .Lxb2_wait
	v_mov_b32_e32 v246, 0x2400
	global_atomic_add v246, v247, s[60:61]
	global_atomic_add v246, v247, s[60:61] offset:256
	global_atomic_add v246, v247, s[60:61] offset:512
	global_atomic_add v246, v247, s[60:61] offset:768
	global_atomic_add v246, v247, s[60:61] offset:1024
	global_atomic_add v246, v247, s[60:61] offset:1280
	global_atomic_add v246, v247, s[60:61] offset:1536
	global_atomic_add v246, v247, s[60:61] offset:1792
	global_atomic_add v246, v247, s[60:61] offset:2048
	global_atomic_add v246, v247, s[60:61] offset:2304
	global_atomic_add v246, v247, s[60:61] offset:2560
	global_atomic_add v246, v247, s[60:61] offset:2816
	global_atomic_add v246, v247, s[60:61] offset:3072
	global_atomic_add v246, v247, s[60:61] offset:3328
	global_atomic_add v246, v247, s[60:61] offset:3584
	global_atomic_add v246, v247, s[60:61] offset:3840
	s_branch .Lxb2_done
